# S5 output stage stagger: waves 4-7 delayed by s_sleep 32
# baseline (speedup 1.0000x reference)
; #define LAS __attribute__((address_space(3)))
; #define S5_LAUNDER() int tid_ = tid0, lane_ = lane0; asm volatile("" : "+v"(tid_), "+v"(lane_)); const int tid = tid_, lane = lane_, fr = lane & 15, fq = lane >> 4; (void)tid; (void)fr; (void)fq
; __device__ __forceinline__ void s5_prompt_item_mfma(LAS unsigned char* lds, int tid0, int lane0, int wave, int n, int g, const bf16* USg, const bf16* FTg, const bf16* WTg, const bf16* GTg, ...
;     ...
;     S5_LAUNDER();
; #pragma unroll
;     for (int it = 0; it < 4; ++it) { const int q = tid + 512 * it; *(LAS v4u*)(lds + R2_OFF + q * 16) = ftq[it]; }
;     const f32x4 dk = *(const f32x4*)(dsk + 4 * fq);
;     __syncthreads();
;     bf16x8 hbv[4][4];
; #pragma unroll
;     for (int kk = 0; kk < 4; ++kk)
; #pragma unroll
;         for (int cb = 0; cb < 4; ++cb) hbv[kk][cb] = *(const LAS bf16x8*)(lds + HP_OFF + (16 * cb + fr) * 272 + 64 * kk + 16 * fq);
.LBB0_852:
	s_or_b64 exec, exec, s[54:55]
	v_mov_b32_e32 v201, v196
	v_mov_b32_e32 v2, v192
	s_lshl_b32 s10, s65, 6
	s_barrier
	s_add_u32 s10, s52, s10
	v_ashrrev_i32_e32 v202, 4, v201
	v_lshlrev_b32_e32 v194, 2, v202
	s_addc_u32 s11, s53, 0
	v_ashrrev_i32_e32 v195, 31, v194
	v_lshl_add_u64 v[20:21], v[194:195], 2, s[10:11]
	global_load_dwordx4 v[20:23], v[20:21], off
	s_add_i32 s10, 0, 0x10800
	v_and_b32_e32 v203, 15, v201
	v_lshl_add_u32 v2, v2, 4, s10
	s_waitcnt vmcnt(20)
	ds_write_b128 v2, v[24:27]
	s_waitcnt vmcnt(19)
	ds_write_b128 v2, v[28:31] offset:8192
	s_waitcnt vmcnt(18)
	ds_write_b128 v2, v[32:35] offset:16384
	s_waitcnt vmcnt(17)
	ds_write_b128 v2, v[36:39] offset:24576
	v_and_b32_e32 v2, -16, v201
	s_add_i32 s11, 0, 0x18c00
	v_mul_u32_u24_e32 v24, 0x110, v203
	v_add3_u32 v2, s11, v2, v24
	s_waitcnt lgkmcnt(0)
	s_barrier
	v_readfirstlane_b32 s99, v192
	s_nop 3
	s_lshr_b32 s99, s99, 6
	s_cmp_lt_u32 s99, 4
	s_cbranch_scc1 .Ls5_stag
	s_sleep 32
